# MLA tile loop: one static s_setprio 1 for waves 4-7 per item, the 12 per-cluster priority flips replaced by s_nop 0 (strategy 4)
# speedup vs baseline: 1.0076x; 1.0076x over previous
.Lmla_item_ready:
	s_cmp_lt_u32 s14, 2
	s_cbranch_scc1 .Lmla_prio_done
	s_setprio 1

.LBB0_1385:
	s_cmp_gt_i32 s21, s17
	s_cbranch_scc1 .LBB0_1391
	s_bitcmp1_b32 s21, 0
	s_cselect_b32 s19, 0xa000, 0
	s_add_i32 s19, s19, 0
	ds_read_b128 v[104:107], v232
	ds_read_b128 v[108:111], v232 offset:1024
	ds_read_b128 v[112:115], v232 offset:2048
	ds_read_b128 v[116:119], v232 offset:3072
	v_add_u32_e32 v120, s19, v165
	v_add_u32_e32 v237, s19, v223
	v_add_u32_e32 v156, v120, v227
	v_add_u32_e32 v158, v120, v229
	v_add_u32_e32 v235, v237, v222
	v_add_u32_e32 v242, s19, v224
	v_add_u32_e32 v157, v120, v228
	ds_read_b128 v[96:99], v156
	ds_read_b128 v[100:103], v157
	v_add_u32_e32 v159, v120, v230
	ds_read_b128 v[120:123], v158
	ds_read_b128 v[124:127], v159
	v_add_u32_e32 v236, v242, v222
	ds_read_b128 v[128:131], v235 offset:16384
	ds_read_b128 v[132:135], v236 offset:16384
	v_xor_b32_e32 v136, 0x80000000, v234
	v_xor_b32_e32 v140, 0x80000000, v233
	v_mov_b32_e32 v137, v136
	v_mov_b32_e32 v138, v136
	v_mov_b32_e32 v139, v136
	v_mov_b32_e32 v141, v140
	v_mov_b32_e32 v142, v140
	v_mov_b32_e32 v143, v140
	s_waitcnt lgkmcnt(0)
	s_nop 0
	v_mfma_f32_16x16x32_bf16 v[144:147], v[96:99], v[40:43], v[136:139]
	v_mfma_f32_16x16x32_bf16 v[96:99], v[96:99], v[56:59], v[140:143]
	ds_read_b128 v[148:151], v156 offset:4096
	v_mfma_f32_16x16x32_bf16 v[144:147], v[100:103], v[44:47], v[144:147]
	v_mfma_f32_16x16x32_bf16 v[96:99], v[100:103], v[60:63], v[96:99]
	ds_read_b128 v[100:103], v157 offset:4096
	v_mfma_f32_16x16x32_bf16 v[144:147], v[120:123], v[48:51], v[144:147]
	v_mfma_f32_16x16x32_bf16 v[96:99], v[120:123], v[64:67], v[96:99]
	ds_read_b128 v[120:123], v158 offset:4096
	v_mfma_f32_16x16x32_bf16 v[144:147], v[124:127], v[52:55], v[144:147]
	v_mfma_f32_16x16x32_bf16 v[96:99], v[124:127], v[68:71], v[96:99]
	ds_read_b128 v[124:127], v159 offset:4096
	v_mfma_f32_16x16x32_bf16 v[144:147], v[128:131], v[104:107], v[144:147]
	v_mfma_f32_16x16x32_bf16 v[96:99], v[128:131], v[112:115], v[96:99]
	ds_read_b128 v[128:131], v235 offset:18432
	v_mfma_f32_16x16x32_bf16 v[144:147], v[132:135], v[108:111], v[144:147]
	v_mfma_f32_16x16x32_bf16 v[96:99], v[132:135], v[116:119], v[96:99]
	ds_read_b128 v[132:135], v236 offset:18432
	s_nop 0
	s_nop 0
	s_waitcnt lgkmcnt(5)
	v_mfma_f32_16x16x32_bf16 v[152:155], v[148:151], v[40:43], v[136:139]
	v_mfma_f32_16x16x32_bf16 v[238:241], v[148:151], v[56:59], v[140:143]
	s_waitcnt lgkmcnt(4)
	v_mfma_f32_16x16x32_bf16 v[152:155], v[100:103], v[44:47], v[152:155]
	v_mfma_f32_16x16x32_bf16 v[238:241], v[100:103], v[60:63], v[238:241]
	s_waitcnt lgkmcnt(3)
	v_mfma_f32_16x16x32_bf16 v[152:155], v[120:123], v[48:51], v[152:155]
	v_mfma_f32_16x16x32_bf16 v[238:241], v[120:123], v[64:67], v[238:241]
	ds_read_b128 v[120:123], v156 offset:8192
	s_waitcnt lgkmcnt(3)
	v_mfma_f32_16x16x32_bf16 v[152:155], v[124:127], v[52:55], v[152:155]
	v_mfma_f32_16x16x32_bf16 v[238:241], v[124:127], v[68:71], v[238:241]
	ds_read_b128 v[124:127], v157 offset:8192
	s_waitcnt lgkmcnt(3)
	v_mfma_f32_16x16x32_bf16 v[152:155], v[128:131], v[104:107], v[152:155]
	v_mfma_f32_16x16x32_bf16 v[238:241], v[128:131], v[112:115], v[238:241]
	ds_read_b128 v[128:131], v158 offset:8192
	s_waitcnt lgkmcnt(3)
	v_mfma_f32_16x16x32_bf16 v[148:151], v[132:135], v[108:111], v[152:155]
	v_mfma_f32_16x16x32_bf16 v[100:103], v[132:135], v[116:119], v[238:241]
	ds_read_b128 v[132:135], v159 offset:8192
	s_nop 0
	s_nop 0
	s_waitcnt lgkmcnt(3)
	v_mfma_f32_16x16x32_bf16 v[238:241], v[120:123], v[40:43], v[136:139]
	v_mfma_f32_16x16x32_bf16 v[120:123], v[120:123], v[56:59], v[140:143]
	ds_read_b128 v[152:155], v235 offset:20480
	s_waitcnt lgkmcnt(3)
	v_mfma_f32_16x16x32_bf16 v[238:241], v[124:127], v[44:47], v[238:241]
	v_mfma_f32_16x16x32_bf16 v[120:123], v[124:127], v[60:63], v[120:123]
	ds_read_b128 v[124:127], v236 offset:20480
	ds_read_b128 v[242:245], v156 offset:12288
	s_waitcnt lgkmcnt(4)
	v_mfma_f32_16x16x32_bf16 v[238:241], v[128:131], v[48:51], v[238:241]
	v_mfma_f32_16x16x32_bf16 v[120:123], v[128:131], v[64:67], v[120:123]
	s_waitcnt lgkmcnt(3)
	v_mfma_f32_16x16x32_bf16 v[238:241], v[132:135], v[52:55], v[238:241]
	v_mfma_f32_16x16x32_bf16 v[120:123], v[132:135], v[68:71], v[120:123]
	ds_read_b128 v[132:135], v157 offset:12288
	s_waitcnt lgkmcnt(3)
	v_mfma_f32_16x16x32_bf16 v[238:241], v[152:155], v[104:107], v[238:241]
	v_mfma_f32_16x16x32_bf16 v[120:123], v[152:155], v[112:115], v[120:123]
	s_waitcnt lgkmcnt(2)
	v_mfma_f32_16x16x32_bf16 v[152:155], v[124:127], v[108:111], v[238:241]
	v_mfma_f32_16x16x32_bf16 v[128:131], v[124:127], v[116:119], v[120:123]
	s_nop 0
	s_nop 4
	ds_read_b128 v[238:241], v158 offset:12288
	ds_read_b128 v[156:159], v159 offset:12288
	ds_read_b128 v[120:123], v235 offset:22528
	ds_read_b128 v[124:127], v236 offset:22528
	s_nop 0
	s_waitcnt lgkmcnt(5)
	v_mfma_f32_16x16x32_bf16 v[136:139], v[242:245], v[40:43], v[136:139]
	v_mfma_f32_16x16x32_bf16 v[242:245], v[242:245], v[56:59], v[140:143]
	s_waitcnt lgkmcnt(4)
	v_mfma_f32_16x16x32_bf16 v[136:139], v[132:135], v[44:47], v[136:139]
	v_mfma_f32_16x16x32_bf16 v[242:245], v[132:135], v[60:63], v[242:245]
	s_waitcnt lgkmcnt(3)
	v_mfma_f32_16x16x32_bf16 v[136:139], v[238:241], v[48:51], v[136:139]
	v_mfma_f32_16x16x32_bf16 v[242:245], v[238:241], v[64:67], v[242:245]
	s_waitcnt lgkmcnt(2)
	v_mfma_f32_16x16x32_bf16 v[136:139], v[156:159], v[52:55], v[136:139]
	v_mfma_f32_16x16x32_bf16 v[242:245], v[156:159], v[68:71], v[242:245]
	s_waitcnt lgkmcnt(1)
	v_mfma_f32_16x16x32_bf16 v[136:139], v[120:123], v[104:107], v[136:139]
	v_mfma_f32_16x16x32_bf16 v[242:245], v[120:123], v[112:115], v[242:245]
	s_waitcnt lgkmcnt(0)
	v_mfma_f32_16x16x32_bf16 v[156:159], v[124:127], v[108:111], v[136:139]
	v_mfma_f32_16x16x32_bf16 v[140:143], v[124:127], v[116:119], v[242:245]
	s_nop 0
	s_nop 2
	ds_read_b128 v[120:123], v235 offset:24576
	ds_read_b128 v[124:127], v235 offset:26624
	ds_read_b128 v[108:111], v236 offset:24576
	ds_read_b128 v[104:107], v236 offset:26624
	ds_read_b128 v[132:135], v235 offset:28672
	ds_read_b128 v[136:139], v235 offset:30720
	ds_read_b128 v[116:119], v236 offset:28672
	ds_read_b128 v[112:115], v236 offset:30720
	v_max3_f32 v239, v144, s27, v145
	v_max3_f32 v239, v239, v146, v147
	v_max3_f32 v239, v239, v148, v149
	v_max3_f32 v239, v239, v150, v151
	v_max3_f32 v239, v239, v152, v153
	v_max3_f32 v239, v239, v154, v155
	v_max3_f32 v239, v239, v156, v157
	v_max3_f32 v239, v239, v158, v159
	s_cmp_eq_u32 s21, 0
	s_cselect_b64 s[38:39], -1, 0
	v_mov_b32_e32 v240, v239
	s_nop 1
	v_permlane16_swap_b32_e32 v240, v239
	v_max_f32_e32 v239, v239, v240
	v_mov_b32_e32 v240, v239
	s_nop 1
	v_permlane32_swap_b32_e32 v240, v239
	v_max_f32_e32 v239, v239, v240
	v_cmp_lt_f32_e32 vcc, s7, v239
	s_or_b64 vcc, s[38:39], vcc
	s_cbranch_vccz .LBB0_1388
	v_max_f32_e32 v240, v239, v239
	v_max_f32_e32 v240, 0, v240
	v_cndmask_b32_e64 v239, v240, v239, s[38:39]
	v_exp_f32_e64 v240, -v239
	v_add_f32_e32 v234, v234, v239
	v_sub_f32_e32 v144, v144, v239
	v_sub_f32_e32 v145, v145, v239
	v_mul_f32_e32 v195, v195, v240
	v_sub_f32_e32 v146, v146, v239
	v_sub_f32_e32 v147, v147, v239
	v_sub_f32_e32 v148, v148, v239
	v_sub_f32_e32 v149, v149, v239
	v_sub_f32_e32 v150, v150, v239
	v_sub_f32_e32 v151, v151, v239
	v_sub_f32_e32 v152, v152, v239
	v_sub_f32_e32 v153, v153, v239
	v_sub_f32_e32 v154, v154, v239
	v_sub_f32_e32 v155, v155, v239
	v_sub_f32_e32 v156, v156, v239
	v_sub_f32_e32 v157, v157, v239
	v_sub_f32_e32 v158, v158, v239
	v_sub_f32_e32 v159, v159, v239
	v_pk_mul_f32 v[94:95], v[94:95], v[240:241] op_sel_hi:[1,0]
	v_pk_mul_f32 v[92:93], v[92:93], v[240:241] op_sel_hi:[1,0]
	v_pk_mul_f32 v[90:91], v[90:91], v[240:241] op_sel_hi:[1,0]
	v_pk_mul_f32 v[88:89], v[88:89], v[240:241] op_sel_hi:[1,0]
	v_pk_mul_f32 v[86:87], v[86:87], v[240:241] op_sel_hi:[1,0]
	v_pk_mul_f32 v[84:85], v[84:85], v[240:241] op_sel_hi:[1,0]
	v_pk_mul_f32 v[82:83], v[82:83], v[240:241] op_sel_hi:[1,0]
	v_pk_mul_f32 v[80:81], v[80:81], v[240:241] op_sel_hi:[1,0]
	v_pk_mul_f32 v[78:79], v[78:79], v[240:241] op_sel_hi:[1,0]
	v_pk_mul_f32 v[76:77], v[76:77], v[240:241] op_sel_hi:[1,0]
	v_pk_mul_f32 v[74:75], v[74:75], v[240:241] op_sel_hi:[1,0]
	v_pk_mul_f32 v[72:73], v[72:73], v[240:241] op_sel_hi:[1,0]
	v_pk_mul_f32 v[38:39], v[38:39], v[240:241] op_sel_hi:[1,0]
	v_pk_mul_f32 v[36:37], v[36:37], v[240:241] op_sel_hi:[1,0]
	v_pk_mul_f32 v[34:35], v[34:35], v[240:241] op_sel_hi:[1,0]
	v_pk_mul_f32 v[32:33], v[32:33], v[240:241] op_sel_hi:[1,0]

.LBB0_1390:
	v_exp_f32_e32 v144, v144
	v_exp_f32_e32 v145, v145
	v_exp_f32_e32 v146, v146
	v_exp_f32_e32 v147, v147
	v_add_f32_e32 v237, 0, v144
	v_exp_f32_e32 v148, v148
	v_add_f32_e32 v237, v237, v145
	v_exp_f32_e32 v149, v149
	v_add_f32_e32 v237, v146, v237
	v_exp_f32_e32 v150, v150
	v_add_f32_e32 v237, v147, v237
	v_exp_f32_e32 v151, v151
	v_add_f32_e32 v237, v148, v237
	v_exp_f32_e32 v152, v152
	v_exp_f32_e32 v153, v153
	v_exp_f32_e32 v96, v96
	v_add_f32_e32 v237, v149, v237
	v_exp_f32_e32 v97, v97
	v_add_f32_e32 v237, v150, v237
	v_exp_f32_e32 v98, v98
	v_add_f32_e32 v237, v151, v237
	v_exp_f32_e32 v99, v99
	v_add_f32_e32 v237, v152, v237
	v_cvt_pk_bf16_f32 v144, v144, v145
	v_cvt_pk_bf16_f32 v145, v146, v147
	v_cvt_pk_bf16_f32 v146, v148, v149
	v_cvt_pk_bf16_f32 v148, v152, v153
	v_add_f32_e32 v152, 0, v96
	v_exp_f32_e32 v100, v100
	v_add_f32_e32 v152, v152, v97
	v_exp_f32_e32 v101, v101
	v_add_f32_e32 v152, v98, v152
	v_exp_f32_e32 v102, v102
	v_add_f32_e32 v152, v99, v152
	v_exp_f32_e32 v103, v103
	v_add_f32_e32 v152, v100, v152
	v_exp_f32_e32 v128, v128
	v_add_f32_e32 v152, v101, v152
	v_exp_f32_e32 v129, v129
	v_exp_f32_e32 v154, v154
	v_add_f32_e32 v152, v102, v152
	v_exp_f32_e32 v130, v130
	v_exp_f32_e32 v155, v155
	v_add_f32_e32 v152, v103, v152
	v_exp_f32_e32 v131, v131
	v_exp_f32_e32 v156, v156
	v_add_f32_e32 v152, v128, v152
	v_exp_f32_e32 v140, v140
	v_add_f32_e32 v237, v153, v237
	v_exp_f32_e32 v157, v157
	v_add_f32_e32 v152, v129, v152
	v_exp_f32_e32 v141, v141
	v_add_f32_e32 v237, v154, v237
	v_exp_f32_e32 v158, v158
	v_add_f32_e32 v152, v130, v152
	v_exp_f32_e32 v142, v142
	v_add_f32_e32 v237, v155, v237
	v_exp_f32_e32 v159, v159
	v_add_f32_e32 v152, v131, v152
	v_exp_f32_e32 v143, v143
	v_add_f32_e32 v237, v156, v237
	v_add_f32_e32 v152, v140, v152
	v_add_f32_e32 v237, v157, v237
	v_add_f32_e32 v152, v141, v152
	v_add_f32_e32 v237, v158, v237
	v_add_f32_e32 v152, v142, v152
	v_add_f32_e32 v237, v159, v237
	v_add_f32_e32 v152, v143, v152
	v_add_f32_e32 v195, v195, v237
	v_add_f32_e32 v193, v193, v152
	v_cvt_pk_bf16_f32 v147, v150, v151
	v_cvt_pk_bf16_f32 v149, v154, v155
	v_cvt_pk_bf16_f32 v150, v156, v157
	v_cvt_pk_bf16_f32 v151, v158, v159
	v_cvt_pk_bf16_f32 v96, v96, v97
	v_cvt_pk_bf16_f32 v97, v98, v99
	v_cvt_pk_bf16_f32 v98, v100, v101
	v_cvt_pk_bf16_f32 v99, v102, v103
	v_cvt_pk_bf16_f32 v100, v128, v129
	v_cvt_pk_bf16_f32 v101, v130, v131
	v_cvt_pk_bf16_f32 v102, v140, v141
	v_cvt_pk_bf16_f32 v103, v142, v143
	s_waitcnt lgkmcnt(0)
	s_nop 0
	v_mfma_f32_16x16x32_bf16 v[92:95], v[120:123], v[144:147], v[92:95]
	v_mfma_f32_16x16x32_bf16 v[28:31], v[120:123], v[96:99], v[28:31]
	ds_read_b128 v[128:131], v235 offset:32768
	v_mfma_f32_16x16x32_bf16 v[88:91], v[124:127], v[144:147], v[88:91]
	v_mfma_f32_16x16x32_bf16 v[24:27], v[124:127], v[96:99], v[24:27]
	ds_read_b128 v[152:155], v235 offset:34816
	v_mfma_f32_16x16x32_bf16 v[84:87], v[132:135], v[144:147], v[84:87]
	v_mfma_f32_16x16x32_bf16 v[20:23], v[132:135], v[96:99], v[20:23]
	ds_read_b128 v[242:245], v235 offset:36864
	v_mfma_f32_16x16x32_bf16 v[80:83], v[136:139], v[144:147], v[80:83]
	v_mfma_f32_16x16x32_bf16 v[16:19], v[136:139], v[96:99], v[16:19]
	ds_read_b128 v[140:143], v235 offset:38912
	v_mfma_f32_16x16x32_bf16 v[92:95], v[108:111], v[148:151], v[92:95]
	v_mfma_f32_16x16x32_bf16 v[28:31], v[108:111], v[100:103], v[28:31]
	ds_read_b128 v[156:159], v236 offset:32768
	v_mfma_f32_16x16x32_bf16 v[88:91], v[104:107], v[148:151], v[88:91]
	v_mfma_f32_16x16x32_bf16 v[24:27], v[104:107], v[100:103], v[24:27]
	ds_read_b128 v[238:241], v236 offset:34816
	v_mfma_f32_16x16x32_bf16 v[84:87], v[116:119], v[148:151], v[84:87]
	v_mfma_f32_16x16x32_bf16 v[20:23], v[116:119], v[100:103], v[20:23]
	ds_read_b128 v[120:123], v236 offset:36864
	v_mfma_f32_16x16x32_bf16 v[80:83], v[112:115], v[148:151], v[80:83]
	v_mfma_f32_16x16x32_bf16 v[16:19], v[112:115], v[100:103], v[16:19]
	ds_read_b128 v[124:127], v236 offset:38912
	s_nop 0
	s_nop 0
	s_waitcnt lgkmcnt(4)
	v_mfma_f32_16x16x32_bf16 v[76:79], v[128:131], v[144:147], v[76:79]
	v_mfma_f32_16x16x32_bf16 v[12:15], v[128:131], v[96:99], v[12:15]
	v_mfma_f32_16x16x32_bf16 v[72:75], v[152:155], v[144:147], v[72:75]
	v_mfma_f32_16x16x32_bf16 v[8:11], v[152:155], v[96:99], v[8:11]
	v_mfma_f32_16x16x32_bf16 v[36:39], v[242:245], v[144:147], v[36:39]
	v_mfma_f32_16x16x32_bf16 v[4:7], v[242:245], v[96:99], v[4:7]
	v_mfma_f32_16x16x32_bf16 v[32:35], v[140:143], v[144:147], v[32:35]
	v_mfma_f32_16x16x32_bf16 v[0:3], v[140:143], v[96:99], v[0:3]
	s_waitcnt lgkmcnt(2)
	v_mfma_f32_16x16x32_bf16 v[76:79], v[156:159], v[148:151], v[76:79]
	v_mfma_f32_16x16x32_bf16 v[12:15], v[156:159], v[100:103], v[12:15]
	v_mfma_f32_16x16x32_bf16 v[72:75], v[238:241], v[148:151], v[72:75]
	v_mfma_f32_16x16x32_bf16 v[8:11], v[238:241], v[100:103], v[8:11]
	s_waitcnt lgkmcnt(0)
	v_mfma_f32_16x16x32_bf16 v[36:39], v[120:123], v[148:151], v[36:39]
	v_mfma_f32_16x16x32_bf16 v[4:7], v[120:123], v[100:103], v[4:7]
	v_mfma_f32_16x16x32_bf16 v[32:35], v[124:127], v[148:151], v[32:35]
	v_mfma_f32_16x16x32_bf16 v[0:3], v[124:127], v[100:103], v[0:3]
	s_nop 0

.LBB0_1393:
	s_setprio 0
	s_barrier
	s_waitcnt vmcnt(0)
	s_barrier
	s_mov_b64 s[4:5], exec
	v_readlane_b32 s8, v248, 2
	v_readlane_b32 s9, v248, 3
	v_readlane_b32 s22, v247, 26
	s_and_b64 s[8:9], s[4:5], s[8:9]
	v_readlane_b32 s23, v247, 27
	s_mov_b64 exec, s[8:9]
	s_cbranch_execz .LBB0_1445
	v_readlane_b32 s3, v248, 57
	s_waitcnt vmcnt(0) expcnt(0) lgkmcnt(0)
	s_nop 0
	v_mov_b32_e32 v0, s3
	ds_read_b32 v2, v0
	v_readlane_b32 s3, v248, 58
	s_waitcnt lgkmcnt(0)
	v_cmp_ne_u32_e32 vcc, 0, v2
	v_mov_b32_e32 v0, s3
	ds_read_b32 v0, v0
	s_cbranch_vccnz .LBB0_1409
	s_mov_b32 s10, 1
	s_branch .LBB0_1397
